# phase E: trailing 8 LDS reads of a tile issued together before their stores (counted lgkmcnt)
# baseline (speedup 1.0000x reference)
.LBB0_1573:
	s_and_b32 s1, s1, s13
	s_lshl_b32 s1, s1, 1
	s_add_u32 s2, s2, s1
	s_addc_u32 s3, s3, 0
	v_lshl_add_u64 v[40:41], s[2:3], 0, v[0:1]
	v_mad_i64_i32 v[42:43], s[2:3], s0, v2, 0
	v_lshl_add_u64 v[42:43], v[42:43], 1, v[40:41]
	s_barrier
	global_load_ushort v216, v[42:43], off
	v_mad_i64_i32 v[42:43], s[2:3], s0, v10, 0
	v_lshl_add_u64 v[42:43], v[42:43], 1, v[40:41]
	s_lshl_b32 s4, s16, 1
	global_load_ushort v217, v[42:43], off
	v_mad_i64_i32 v[42:43], s[2:3], s0, v12, 0
	v_lshl_add_u64 v[42:43], v[42:43], 1, v[40:41]
	global_load_ushort v218, v[42:43], off
	v_mad_i64_i32 v[42:43], s[2:3], s0, v14, 0
	v_lshl_add_u64 v[42:43], v[42:43], 1, v[40:41]
	global_load_ushort v219, v[42:43], off
	v_mad_i64_i32 v[42:43], s[2:3], s0, v16, 0
	v_lshl_add_u64 v[42:43], v[42:43], 1, v[40:41]
	global_load_ushort v220, v[42:43], off
	v_mad_i64_i32 v[42:43], s[2:3], s0, v18, 0
	v_lshl_add_u64 v[42:43], v[42:43], 1, v[40:41]
	global_load_ushort v221, v[42:43], off
	v_mad_i64_i32 v[42:43], s[2:3], s0, v20, 0
	v_lshl_add_u64 v[42:43], v[42:43], 1, v[40:41]
	global_load_ushort v222, v[42:43], off
	v_mad_i64_i32 v[42:43], s[2:3], s0, v22, 0
	v_lshl_add_u64 v[42:43], v[42:43], 1, v[40:41]
	global_load_ushort v223, v[42:43], off
	v_mad_i64_i32 v[42:43], s[2:3], s0, v24, 0
	v_lshl_add_u64 v[42:43], v[42:43], 1, v[40:41]
	global_load_ushort v224, v[42:43], off
	v_mad_i64_i32 v[42:43], s[2:3], s0, v26, 0
	v_lshl_add_u64 v[42:43], v[42:43], 1, v[40:41]
	global_load_ushort v225, v[42:43], off
	v_mad_i64_i32 v[42:43], s[2:3], s0, v28, 0
	v_lshl_add_u64 v[42:43], v[42:43], 1, v[40:41]
	global_load_ushort v226, v[42:43], off
	v_mad_i64_i32 v[42:43], s[2:3], s0, v30, 0
	v_lshl_add_u64 v[42:43], v[42:43], 1, v[40:41]
	global_load_ushort v227, v[42:43], off
	v_mad_i64_i32 v[42:43], s[2:3], s0, v32, 0
	v_lshl_add_u64 v[42:43], v[42:43], 1, v[40:41]
	global_load_ushort v228, v[42:43], off
	v_mad_i64_i32 v[42:43], s[2:3], s0, v34, 0
	v_lshl_add_u64 v[42:43], v[42:43], 1, v[40:41]
	global_load_ushort v229, v[42:43], off
	v_mad_i64_i32 v[42:43], s[2:3], s0, v36, 0
	v_lshl_add_u64 v[42:43], v[42:43], 1, v[40:41]
	global_load_ushort v230, v[42:43], off
	v_mad_i64_i32 v[42:43], s[0:1], s0, v38, 0
	v_lshl_add_u64 v[40:41], v[42:43], 1, v[40:41]
	v_add_u32_e32 v42, s15, v2
	v_ashrrev_i32_e32 v43, 31, v42
	v_lshlrev_b64 v[42:43], 10, v[42:43]
	v_readlane_b32 s0, v253, 1
	s_add_i32 s6, s6, s0
	v_readlane_b32 s0, v255, 8
	s_add_i32 s13, s13, s0
	v_readlane_b32 s0, v255, 9
	s_add_i32 s14, s14, s0
	s_cmpk_gt_i32 s6, 0x5ff
	v_readlane_b32 s1, v253, 2
	global_load_ushort v231, v[40:41], off
	v_lshl_add_u64 v[40:41], v[8:9], 0, s[4:5]
	v_lshl_add_u64 v[42:43], v[40:41], 0, v[42:43]
	s_waitcnt vmcnt(15)
	ds_write_b16 v11, v216
	s_waitcnt vmcnt(14)
	ds_write_b16 v11, v217 offset:528
	s_waitcnt vmcnt(13)
	ds_write_b16 v11, v218 offset:1056
	s_waitcnt vmcnt(12)
	ds_write_b16 v11, v219 offset:1584
	s_waitcnt vmcnt(11)
	ds_write_b16 v11, v220 offset:2112
	s_waitcnt vmcnt(10)
	ds_write_b16 v11, v221 offset:2640
	s_waitcnt vmcnt(9)
	ds_write_b16 v11, v222 offset:3168
	s_waitcnt vmcnt(8)
	ds_write_b16 v11, v223 offset:3696
	s_waitcnt vmcnt(7)
	ds_write_b16 v11, v224 offset:4224
	s_waitcnt vmcnt(6)
	ds_write_b16 v11, v225 offset:4752
	s_waitcnt vmcnt(5)
	ds_write_b16 v11, v226 offset:5280
	s_waitcnt vmcnt(4)
	ds_write_b16 v11, v227 offset:5808
	s_waitcnt vmcnt(3)
	ds_write_b16 v11, v228 offset:6336
	s_waitcnt vmcnt(2)
	ds_write_b16 v11, v229 offset:6864
	s_waitcnt vmcnt(1)
	ds_write_b16 v11, v230 offset:7392
	s_waitcnt vmcnt(0)
	ds_write_b16 v11, v231 offset:7920
	s_waitcnt lgkmcnt(0)
	s_barrier
	ds_read_u16 v13, v3
	ds_read_u16 v15, v3 offset:8
	ds_read_u16 v17, v3 offset:16
	ds_read_u16 v19, v3 offset:24
	ds_read_u16 v21, v3 offset:32
	ds_read_u16 v23, v3 offset:40
	ds_read_u16 v25, v3 offset:48
	ds_read_u16 v27, v3 offset:56
	s_waitcnt lgkmcnt(7)
	global_store_short v[42:43], v13, off
	v_add_u32_e32 v42, s15, v10
	v_ashrrev_i32_e32 v43, 31, v42
	v_lshlrev_b64 v[42:43], 10, v[42:43]
	v_lshl_add_u64 v[42:43], v[40:41], 0, v[42:43]
	s_waitcnt lgkmcnt(6)
	global_store_short v[42:43], v15, off
	v_add_u32_e32 v42, s15, v12
	v_ashrrev_i32_e32 v43, 31, v42
	v_lshlrev_b64 v[42:43], 10, v[42:43]
	v_lshl_add_u64 v[42:43], v[40:41], 0, v[42:43]
	s_waitcnt lgkmcnt(5)
	global_store_short v[42:43], v17, off
	v_add_u32_e32 v42, s15, v14
	v_ashrrev_i32_e32 v43, 31, v42
	v_lshlrev_b64 v[42:43], 10, v[42:43]
	v_lshl_add_u64 v[42:43], v[40:41], 0, v[42:43]
	s_waitcnt lgkmcnt(4)
	global_store_short v[42:43], v19, off
	v_add_u32_e32 v42, s15, v16
	v_ashrrev_i32_e32 v43, 31, v42
	v_lshlrev_b64 v[42:43], 10, v[42:43]
	v_lshl_add_u64 v[42:43], v[40:41], 0, v[42:43]
	s_waitcnt lgkmcnt(3)
	global_store_short v[42:43], v21, off
	v_add_u32_e32 v42, s15, v18
	v_ashrrev_i32_e32 v43, 31, v42
	v_lshlrev_b64 v[42:43], 10, v[42:43]
	v_lshl_add_u64 v[42:43], v[40:41], 0, v[42:43]
	s_waitcnt lgkmcnt(2)
	global_store_short v[42:43], v23, off
	v_add_u32_e32 v42, s15, v20
	v_ashrrev_i32_e32 v43, 31, v42
	v_lshlrev_b64 v[42:43], 10, v[42:43]
	v_lshl_add_u64 v[42:43], v[40:41], 0, v[42:43]
	s_waitcnt lgkmcnt(1)
	global_store_short v[42:43], v25, off
	v_add_u32_e32 v42, s15, v22
	v_ashrrev_i32_e32 v43, 31, v42
	v_lshlrev_b64 v[42:43], 10, v[42:43]
	v_lshl_add_u64 v[42:43], v[40:41], 0, v[42:43]
	ds_read_u16 v232, v3 offset:64
	ds_read_u16 v233, v3 offset:72
	ds_read_u16 v234, v3 offset:80
	ds_read_u16 v235, v3 offset:88
	ds_read_u16 v236, v3 offset:96
	ds_read_u16 v237, v3 offset:104
	ds_read_u16 v238, v3 offset:112
	ds_read_u16 v239, v3 offset:120
	s_waitcnt lgkmcnt(8)
	global_store_short v[42:43], v27, off
	v_add_u32_e32 v42, s15, v24
	v_ashrrev_i32_e32 v43, 31, v42
	v_lshlrev_b64 v[42:43], 10, v[42:43]
	v_lshl_add_u64 v[42:43], v[40:41], 0, v[42:43]
	s_waitcnt lgkmcnt(7)
	global_store_short v[42:43], v232, off
	v_add_u32_e32 v42, s15, v26
	v_ashrrev_i32_e32 v43, 31, v42
	v_lshlrev_b64 v[42:43], 10, v[42:43]
	v_lshl_add_u64 v[42:43], v[40:41], 0, v[42:43]
	s_waitcnt lgkmcnt(6)
	global_store_short v[42:43], v233, off
	v_add_u32_e32 v42, s15, v28
	v_ashrrev_i32_e32 v43, 31, v42
	v_lshlrev_b64 v[42:43], 10, v[42:43]
	v_lshl_add_u64 v[42:43], v[40:41], 0, v[42:43]
	s_waitcnt lgkmcnt(5)
	global_store_short v[42:43], v234, off
	v_add_u32_e32 v42, s15, v30
	v_ashrrev_i32_e32 v43, 31, v42
	v_lshlrev_b64 v[42:43], 10, v[42:43]
	v_lshl_add_u64 v[42:43], v[40:41], 0, v[42:43]
	s_waitcnt lgkmcnt(4)
	global_store_short v[42:43], v235, off
	v_add_u32_e32 v42, s15, v32
	v_ashrrev_i32_e32 v43, 31, v42
	v_lshlrev_b64 v[42:43], 10, v[42:43]
	v_lshl_add_u64 v[42:43], v[40:41], 0, v[42:43]
	s_waitcnt lgkmcnt(3)
	global_store_short v[42:43], v236, off
	v_add_u32_e32 v42, s15, v34
	v_ashrrev_i32_e32 v43, 31, v42
	v_lshlrev_b64 v[42:43], 10, v[42:43]
	v_lshl_add_u64 v[42:43], v[40:41], 0, v[42:43]
	s_waitcnt lgkmcnt(2)
	global_store_short v[42:43], v237, off
	v_add_u32_e32 v42, s15, v36
	v_ashrrev_i32_e32 v43, 31, v42
	v_lshlrev_b64 v[42:43], 10, v[42:43]
	v_lshl_add_u64 v[42:43], v[40:41], 0, v[42:43]
	s_waitcnt lgkmcnt(1)
	global_store_short v[42:43], v238, off
	v_add_u32_e32 v42, s15, v38
	v_ashrrev_i32_e32 v43, 31, v42
	v_lshlrev_b64 v[42:43], 10, v[42:43]
	v_lshl_add_u64 v[40:41], v[40:41], 0, v[42:43]
	s_waitcnt lgkmcnt(0)
	global_store_short v[40:41], v239, off
	s_cbranch_scc1 .LBB0_1578
